# v49: workgroups that do not consume the second exchange's totals (pn != 0) publish their partial and skip the wait
# baseline (speedup 1.0000x reference)
.LBB0_713:
	s_or_b64 exec, exec, s[6:7]
	s_cmp_lg_u32 s18, 0
	s_cbranch_scc1 .LBB0_719
	s_andn2_b64 vcc, exec, s[0:1]
	s_cbranch_vccnz .LBB0_719
	s_lshl_b32 s0, s28, 6
	s_ashr_i32 s1, s0, 31
	s_add_i32 s34, s34, 64
	s_lshl_b64 s[0:1], s[0:1], 2
	s_add_u32 s0, s29, s0
	s_addc_u32 s1, s30, s1
	v_mov_b32_e32 v3, 0x100000
	s_branch .LBB0_716
